# P3 indexer: full 64-key blocks of a query's keys read straight from the LDS key matrix via one lane-address register
# speedup vs baseline: 1.0284x; 1.0028x over previous
.LBB0_654:
	s_xor_b64 s[0:1], s[0:1], -1
	v_writelane_b32 v254, s0, 49
	s_waitcnt lgkmcnt(0)
	s_barrier
	v_lshl_add_u32 v255, v130, 2, s7
	v_writelane_b32 v254, s1, 50
	s_add_i32 s0, s79, 16
	s_cmp_gt_i32 s0, 0
	s_cselect_b64 s[8:9], -1, 0
	s_cmp_lt_i32 s0, 1
	s_cbranch_scc1 .LBB0_656
	s_cmpk_lt_i32 s0, 0x40
	s_cbranch_scc1 .Lkg_1
	ds_read_b32 v245, v255 offset:8448
	ds_read_b32 v215, v255 offset:16656
	s_branch .Lkd_1
.Lkg_1:
	v_cmp_gt_i32_e32 vcc, s0, v130
	s_nop 1
	v_cndmask_b32_e32 v76, 0, v130, vcc
	v_lshl_add_u32 v76, v76, 2, s7
	ds_read_b32 v77, v76 offset:8448
	ds_read_b32 v76, v76 offset:16656
	s_waitcnt lgkmcnt(1)
	v_cndmask_b32_e32 v245, 0, v77, vcc
	s_waitcnt lgkmcnt(0)
	v_cndmask_b32_e32 v215, 0, v76, vcc
.Lkd_1:
	s_branch .LBB0_657
.LBB0_656:
	v_mov_b32_e32 v245, 0
	v_mov_b32_e32 v215, 0
.LBB0_657:
	v_mov_b32_e32 v243, 0
	s_cmpk_lt_i32 s0, 0x41
	v_mov_b32_e32 v244, 0
	v_mov_b32_e32 v108, 0
	s_cbranch_scc1 .LBB0_659
	s_cmpk_lt_i32 s0, 0x80
	s_cbranch_scc1 .Lkg_2
	ds_read_b32 v244, v255 offset:8704
	ds_read_b32 v108, v255 offset:16912
	s_branch .Lkd_2
.Lkg_2:
	v_cmp_gt_i32_e32 vcc, s0, v168
	s_nop 1
	v_cndmask_b32_e32 v76, 0, v168, vcc
	v_lshl_add_u32 v76, v76, 2, s7
	ds_read_b32 v77, v76 offset:8448
	ds_read_b32 v76, v76 offset:16656
	s_waitcnt lgkmcnt(1)
	v_cndmask_b32_e32 v244, 0, v77, vcc
	s_waitcnt lgkmcnt(0)
	v_cndmask_b32_e32 v108, 0, v76, vcc
.Lkd_2:
.LBB0_659:
	s_cmpk_lt_i32 s0, 0x81
	v_mov_b32_e32 v107, 0
	s_cbranch_scc1 .LBB0_661
	s_cmpk_lt_i32 s0, 0xc0
	s_cbranch_scc1 .Lkg_3
	ds_read_b32 v243, v255 offset:8960
	ds_read_b32 v107, v255 offset:17168
	s_branch .Lkd_3
.Lkg_3:
	v_cmp_gt_i32_e32 vcc, s0, v169
	s_nop 1
	v_cndmask_b32_e32 v76, 0, v169, vcc
	v_lshl_add_u32 v76, v76, 2, s7
	ds_read_b32 v77, v76 offset:8448
	ds_read_b32 v76, v76 offset:16656
	s_waitcnt lgkmcnt(1)
	v_cndmask_b32_e32 v243, 0, v77, vcc
	s_waitcnt lgkmcnt(0)
	v_cndmask_b32_e32 v107, 0, v76, vcc
.Lkd_3:
.LBB0_661:
	v_mov_b32_e32 v241, 0
	s_cmpk_lt_i32 s0, 0xc1
	v_mov_b32_e32 v242, 0
	v_mov_b32_e32 v106, 0
	s_cbranch_scc1 .LBB0_663
	s_cmpk_lt_i32 s0, 0x100
	s_cbranch_scc1 .Lkg_4
	ds_read_b32 v242, v255 offset:9216
	ds_read_b32 v106, v255 offset:17424
	s_branch .Lkd_4
.Lkg_4:
	v_cmp_gt_i32_e32 vcc, s0, v170
	s_nop 1
	v_cndmask_b32_e32 v76, 0, v170, vcc
	v_lshl_add_u32 v76, v76, 2, s7
	ds_read_b32 v77, v76 offset:8448
	ds_read_b32 v76, v76 offset:16656
	s_waitcnt lgkmcnt(1)
	v_cndmask_b32_e32 v242, 0, v77, vcc
	s_waitcnt lgkmcnt(0)
	v_cndmask_b32_e32 v106, 0, v76, vcc
.Lkd_4:
.LBB0_663:
	s_cmpk_lt_i32 s0, 0x101
	v_mov_b32_e32 v105, 0
	s_cbranch_scc1 .LBB0_665
	s_cmpk_lt_i32 s0, 0x140
	s_cbranch_scc1 .Lkg_5
	ds_read_b32 v241, v255 offset:9472
	ds_read_b32 v105, v255 offset:17680
	s_branch .Lkd_5
.Lkg_5:
	v_cmp_gt_i32_e32 vcc, s0, v171
	s_nop 1
	v_cndmask_b32_e32 v76, 0, v171, vcc
	v_lshl_add_u32 v76, v76, 2, s7
	ds_read_b32 v77, v76 offset:8448
	ds_read_b32 v76, v76 offset:16656
	s_waitcnt lgkmcnt(1)
	v_cndmask_b32_e32 v241, 0, v77, vcc
	s_waitcnt lgkmcnt(0)
	v_cndmask_b32_e32 v105, 0, v76, vcc
.Lkd_5:
.LBB0_665:
	v_mov_b32_e32 v239, 0
	s_cmpk_lt_i32 s0, 0x141
	v_mov_b32_e32 v240, 0
	v_mov_b32_e32 v104, 0
	s_cbranch_scc1 .LBB0_667
	s_cmpk_lt_i32 s0, 0x180
	s_cbranch_scc1 .Lkg_6
	ds_read_b32 v240, v255 offset:9728
	ds_read_b32 v104, v255 offset:17936
	s_branch .Lkd_6
.Lkg_6:
	v_cmp_gt_i32_e32 vcc, s0, v172
	s_nop 1
	v_cndmask_b32_e32 v76, 0, v172, vcc
	v_lshl_add_u32 v76, v76, 2, s7
	ds_read_b32 v77, v76 offset:8448
	ds_read_b32 v76, v76 offset:16656
	s_waitcnt lgkmcnt(1)
	v_cndmask_b32_e32 v240, 0, v77, vcc
	s_waitcnt lgkmcnt(0)
	v_cndmask_b32_e32 v104, 0, v76, vcc
.Lkd_6:
.LBB0_667:
	s_cmpk_lt_i32 s0, 0x181
	v_mov_b32_e32 v103, 0
	s_cbranch_scc1 .LBB0_669
	s_cmpk_lt_i32 s0, 0x1c0
	s_cbranch_scc1 .Lkg_7
	ds_read_b32 v239, v255 offset:9984
	ds_read_b32 v103, v255 offset:18192
	s_branch .Lkd_7
.Lkg_7:
	v_cmp_gt_i32_e32 vcc, s0, v173
	s_nop 1
	v_cndmask_b32_e32 v76, 0, v173, vcc
	v_lshl_add_u32 v76, v76, 2, s7
	ds_read_b32 v77, v76 offset:8448
	ds_read_b32 v76, v76 offset:16656
	s_waitcnt lgkmcnt(1)
	v_cndmask_b32_e32 v239, 0, v77, vcc
	s_waitcnt lgkmcnt(0)
	v_cndmask_b32_e32 v103, 0, v76, vcc
.Lkd_7:
.LBB0_669:
	v_mov_b32_e32 v237, 0
	s_cmpk_lt_i32 s0, 0x1c1
	v_mov_b32_e32 v238, 0
	v_mov_b32_e32 v102, 0
	s_cbranch_scc1 .LBB0_671
	s_cmpk_lt_i32 s0, 0x200
	s_cbranch_scc1 .Lkg_8
	ds_read_b32 v238, v255 offset:10240
	ds_read_b32 v102, v255 offset:18448
	s_branch .Lkd_8
.Lkg_8:
	v_cmp_gt_i32_e32 vcc, s0, v174
	s_nop 1
	v_cndmask_b32_e32 v76, 0, v174, vcc
	v_lshl_add_u32 v76, v76, 2, s7
	ds_read_b32 v77, v76 offset:8448
	ds_read_b32 v76, v76 offset:16656
	s_waitcnt lgkmcnt(1)
	v_cndmask_b32_e32 v238, 0, v77, vcc
	s_waitcnt lgkmcnt(0)
	v_cndmask_b32_e32 v102, 0, v76, vcc
.Lkd_8:
.LBB0_671:
	s_cmpk_gt_i32 s0, 0x200
	s_cselect_b64 s[10:11], -1, 0
	s_cmpk_lt_i32 s0, 0x201
	v_mov_b32_e32 v101, 0
	s_cbranch_scc1 .LBB0_673
	s_cmpk_lt_i32 s0, 0x240
	s_cbranch_scc1 .Lkg_9
	ds_read_b32 v237, v255 offset:10496
	ds_read_b32 v101, v255 offset:18704
	s_branch .Lkd_9
.Lkg_9:
	v_cmp_gt_i32_e32 vcc, s0, v175
	s_nop 1
	v_cndmask_b32_e32 v76, 0, v175, vcc
	v_lshl_add_u32 v76, v76, 2, s7
	ds_read_b32 v77, v76 offset:8448
	ds_read_b32 v76, v76 offset:16656
	s_waitcnt lgkmcnt(1)
	v_cndmask_b32_e32 v237, 0, v77, vcc
	s_waitcnt lgkmcnt(0)
	v_cndmask_b32_e32 v101, 0, v76, vcc
.Lkd_9:
.LBB0_673:
	v_mov_b32_e32 v235, 0
	s_cmpk_lt_i32 s0, 0x241
	v_mov_b32_e32 v236, 0
	v_mov_b32_e32 v100, 0
	s_cbranch_scc1 .LBB0_675
	s_cmpk_lt_i32 s0, 0x280
	s_cbranch_scc1 .Lkg_10
	ds_read_b32 v236, v255 offset:10752
	ds_read_b32 v100, v255 offset:18960
	s_branch .Lkd_10
.Lkg_10:
	v_cmp_gt_i32_e32 vcc, s0, v176
	s_nop 1
	v_cndmask_b32_e32 v76, 0, v176, vcc
	v_lshl_add_u32 v76, v76, 2, s7
	ds_read_b32 v77, v76 offset:8448
	ds_read_b32 v76, v76 offset:16656
	s_waitcnt lgkmcnt(1)
	v_cndmask_b32_e32 v236, 0, v77, vcc
	s_waitcnt lgkmcnt(0)
	v_cndmask_b32_e32 v100, 0, v76, vcc
.Lkd_10:
.LBB0_675:
	s_cmpk_lt_i32 s0, 0x281
	v_mov_b32_e32 v99, 0
	s_cbranch_scc1 .LBB0_677
	s_cmpk_lt_i32 s0, 0x2c0
	s_cbranch_scc1 .Lkg_11
	ds_read_b32 v235, v255 offset:11008
	ds_read_b32 v99, v255 offset:19216
	s_branch .Lkd_11
.Lkg_11:
	v_cmp_gt_i32_e32 vcc, s0, v177
	s_nop 1
	v_cndmask_b32_e32 v76, 0, v177, vcc
	v_lshl_add_u32 v76, v76, 2, s7
	ds_read_b32 v77, v76 offset:8448
	ds_read_b32 v76, v76 offset:16656
	s_waitcnt lgkmcnt(1)
	v_cndmask_b32_e32 v235, 0, v77, vcc
	s_waitcnt lgkmcnt(0)
	v_cndmask_b32_e32 v99, 0, v76, vcc
.Lkd_11:
.LBB0_677:
	v_mov_b32_e32 v233, 0
	s_cmpk_lt_i32 s0, 0x2c1
	v_mov_b32_e32 v234, 0
	v_mov_b32_e32 v98, 0
	s_cbranch_scc1 .LBB0_679
	s_cmpk_lt_i32 s0, 0x300
	s_cbranch_scc1 .Lkg_12
	ds_read_b32 v234, v255 offset:11264
	ds_read_b32 v98, v255 offset:19472
	s_branch .Lkd_12
.Lkg_12:
	v_cmp_gt_i32_e32 vcc, s0, v178
	s_nop 1
	v_cndmask_b32_e32 v76, 0, v178, vcc
	v_lshl_add_u32 v76, v76, 2, s7
	ds_read_b32 v77, v76 offset:8448
	ds_read_b32 v76, v76 offset:16656
	s_waitcnt lgkmcnt(1)
	v_cndmask_b32_e32 v234, 0, v77, vcc
	s_waitcnt lgkmcnt(0)
	v_cndmask_b32_e32 v98, 0, v76, vcc
.Lkd_12:
.LBB0_679:
	s_cmpk_lt_i32 s0, 0x301
	v_mov_b32_e32 v97, 0
	s_cbranch_scc1 .LBB0_681
	s_cmpk_lt_i32 s0, 0x340
	s_cbranch_scc1 .Lkg_13
	ds_read_b32 v233, v255 offset:11520
	ds_read_b32 v97, v255 offset:19728
	s_branch .Lkd_13
.Lkg_13:
	v_cmp_gt_i32_e32 vcc, s0, v179
	s_nop 1
	v_cndmask_b32_e32 v76, 0, v179, vcc
	v_lshl_add_u32 v76, v76, 2, s7
	ds_read_b32 v77, v76 offset:8448
	ds_read_b32 v76, v76 offset:16656
	s_waitcnt lgkmcnt(1)
	v_cndmask_b32_e32 v233, 0, v77, vcc
	s_waitcnt lgkmcnt(0)
	v_cndmask_b32_e32 v97, 0, v76, vcc
.Lkd_13:
.LBB0_681:
	v_mov_b32_e32 v231, 0
	s_cmpk_lt_i32 s0, 0x341
	v_mov_b32_e32 v232, 0
	v_mov_b32_e32 v96, 0
	s_cbranch_scc1 .LBB0_683
	s_cmpk_lt_i32 s0, 0x380
	s_cbranch_scc1 .Lkg_14
	ds_read_b32 v232, v255 offset:11776
	ds_read_b32 v96, v255 offset:19984
	s_branch .Lkd_14
.Lkg_14:
	v_cmp_gt_i32_e32 vcc, s0, v180
	s_nop 1
	v_cndmask_b32_e32 v76, 0, v180, vcc
	v_lshl_add_u32 v76, v76, 2, s7
	ds_read_b32 v77, v76 offset:8448
	ds_read_b32 v76, v76 offset:16656
	s_waitcnt lgkmcnt(1)
	v_cndmask_b32_e32 v232, 0, v77, vcc
	s_waitcnt lgkmcnt(0)
	v_cndmask_b32_e32 v96, 0, v76, vcc
.Lkd_14:
.LBB0_683:
	s_cmpk_lt_i32 s0, 0x381
	v_mov_b32_e32 v95, 0
	s_cbranch_scc1 .LBB0_685
	s_cmpk_lt_i32 s0, 0x3c0
	s_cbranch_scc1 .Lkg_15
	ds_read_b32 v231, v255 offset:12032
	ds_read_b32 v95, v255 offset:20240
	s_branch .Lkd_15
.Lkg_15:
	v_cmp_gt_i32_e32 vcc, s0, v181
	s_nop 1
	v_cndmask_b32_e32 v76, 0, v181, vcc
	v_lshl_add_u32 v76, v76, 2, s7
	ds_read_b32 v77, v76 offset:8448
	ds_read_b32 v76, v76 offset:16656
	s_waitcnt lgkmcnt(1)
	v_cndmask_b32_e32 v231, 0, v77, vcc
	s_waitcnt lgkmcnt(0)
	v_cndmask_b32_e32 v95, 0, v76, vcc
.Lkd_15:
.LBB0_685:
	v_mov_b32_e32 v229, 0
	s_cmpk_lt_i32 s0, 0x3c1
	v_mov_b32_e32 v230, 0
	v_mov_b32_e32 v94, 0
	s_cbranch_scc1 .LBB0_687
	s_cmpk_lt_i32 s0, 0x400
	s_cbranch_scc1 .Lkg_16
	ds_read_b32 v230, v255 offset:12288
	ds_read_b32 v94, v255 offset:20496
	s_branch .Lkd_16
.Lkg_16:
	v_cmp_gt_i32_e32 vcc, s0, v182
	s_nop 1
	v_cndmask_b32_e32 v76, 0, v182, vcc
	v_lshl_add_u32 v76, v76, 2, s7
	ds_read_b32 v77, v76 offset:8448
	ds_read_b32 v76, v76 offset:16656
	s_waitcnt lgkmcnt(1)
	v_cndmask_b32_e32 v230, 0, v77, vcc
	s_waitcnt lgkmcnt(0)
	v_cndmask_b32_e32 v94, 0, v76, vcc
.Lkd_16:
.LBB0_687:
	s_cmpk_gt_i32 s0, 0x400
	s_cselect_b64 s[12:13], -1, 0
	s_cmpk_lt_i32 s0, 0x401
	v_mov_b32_e32 v93, 0
	s_cbranch_scc1 .LBB0_689
	s_cmpk_lt_i32 s0, 0x440
	s_cbranch_scc1 .Lkg_17
	ds_read_b32 v229, v255 offset:12544
	ds_read_b32 v93, v255 offset:20752
	s_branch .Lkd_17
.Lkg_17:
	v_cmp_gt_i32_e32 vcc, s0, v183
	s_nop 1
	v_cndmask_b32_e32 v76, 0, v183, vcc
	v_lshl_add_u32 v76, v76, 2, s7
	ds_read_b32 v77, v76 offset:8448
	ds_read_b32 v76, v76 offset:16656
	s_waitcnt lgkmcnt(1)
	v_cndmask_b32_e32 v229, 0, v77, vcc
	s_waitcnt lgkmcnt(0)
	v_cndmask_b32_e32 v93, 0, v76, vcc
.Lkd_17:
.LBB0_689:
	v_mov_b32_e32 v227, 0
	s_cmpk_lt_i32 s0, 0x441
	v_mov_b32_e32 v228, 0
	v_mov_b32_e32 v92, 0
	s_cbranch_scc1 .LBB0_691
	s_cmpk_lt_i32 s0, 0x480
	s_cbranch_scc1 .Lkg_18
	ds_read_b32 v228, v255 offset:12800
	ds_read_b32 v92, v255 offset:21008
	s_branch .Lkd_18
.Lkg_18:
	v_cmp_gt_i32_e32 vcc, s0, v184
	s_nop 1
	v_cndmask_b32_e32 v76, 0, v184, vcc
	v_lshl_add_u32 v76, v76, 2, s7
	ds_read_b32 v77, v76 offset:8448
	ds_read_b32 v76, v76 offset:16656
	s_waitcnt lgkmcnt(1)
	v_cndmask_b32_e32 v228, 0, v77, vcc
	s_waitcnt lgkmcnt(0)
	v_cndmask_b32_e32 v92, 0, v76, vcc
.Lkd_18:
.LBB0_691:
	s_cmpk_lt_i32 s0, 0x481
	v_mov_b32_e32 v91, 0
	s_cbranch_scc1 .LBB0_693
	s_cmpk_lt_i32 s0, 0x4c0
	s_cbranch_scc1 .Lkg_19
	ds_read_b32 v227, v255 offset:13056
	ds_read_b32 v91, v255 offset:21264
	s_branch .Lkd_19
.Lkg_19:
	v_cmp_gt_i32_e32 vcc, s0, v185
	s_nop 1
	v_cndmask_b32_e32 v76, 0, v185, vcc
	v_lshl_add_u32 v76, v76, 2, s7
	ds_read_b32 v77, v76 offset:8448
	ds_read_b32 v76, v76 offset:16656
	s_waitcnt lgkmcnt(1)
	v_cndmask_b32_e32 v227, 0, v77, vcc
	s_waitcnt lgkmcnt(0)
	v_cndmask_b32_e32 v91, 0, v76, vcc
.Lkd_19:
.LBB0_693:
	v_mov_b32_e32 v225, 0
	s_cmpk_lt_i32 s0, 0x4c1
	v_mov_b32_e32 v226, 0
	v_mov_b32_e32 v90, 0
	s_cbranch_scc1 .LBB0_695
	s_cmpk_lt_i32 s0, 0x500
	s_cbranch_scc1 .Lkg_20
	ds_read_b32 v226, v255 offset:13312
	ds_read_b32 v90, v255 offset:21520
	s_branch .Lkd_20
.Lkg_20:
	v_cmp_gt_i32_e32 vcc, s0, v186
	s_nop 1
	v_cndmask_b32_e32 v76, 0, v186, vcc
	v_lshl_add_u32 v76, v76, 2, s7
	ds_read_b32 v77, v76 offset:8448
	ds_read_b32 v76, v76 offset:16656
	s_waitcnt lgkmcnt(1)
	v_cndmask_b32_e32 v226, 0, v77, vcc
	s_waitcnt lgkmcnt(0)
	v_cndmask_b32_e32 v90, 0, v76, vcc
.Lkd_20:
.LBB0_695:
	s_cmpk_lt_i32 s0, 0x501
	v_mov_b32_e32 v89, 0
	s_cbranch_scc1 .LBB0_697
	s_cmpk_lt_i32 s0, 0x540
	s_cbranch_scc1 .Lkg_21
	ds_read_b32 v225, v255 offset:13568
	ds_read_b32 v89, v255 offset:21776
	s_branch .Lkd_21
.Lkg_21:
	v_cmp_gt_i32_e32 vcc, s0, v187
	s_nop 1
	v_cndmask_b32_e32 v76, 0, v187, vcc
	v_lshl_add_u32 v76, v76, 2, s7
	ds_read_b32 v77, v76 offset:8448
	ds_read_b32 v76, v76 offset:16656
	s_waitcnt lgkmcnt(1)
	v_cndmask_b32_e32 v225, 0, v77, vcc
	s_waitcnt lgkmcnt(0)
	v_cndmask_b32_e32 v89, 0, v76, vcc
.Lkd_21:
.LBB0_697:
	v_mov_b32_e32 v223, 0
	s_cmpk_lt_i32 s0, 0x541
	v_mov_b32_e32 v224, 0
	v_mov_b32_e32 v88, 0
	s_cbranch_scc1 .LBB0_699
	s_cmpk_lt_i32 s0, 0x580
	s_cbranch_scc1 .Lkg_22
	ds_read_b32 v224, v255 offset:13824
	ds_read_b32 v88, v255 offset:22032
	s_branch .Lkd_22
.Lkg_22:
	v_cmp_gt_i32_e32 vcc, s0, v202
	s_nop 1
	v_cndmask_b32_e32 v76, 0, v202, vcc
	v_lshl_add_u32 v76, v76, 2, s7
	ds_read_b32 v77, v76 offset:8448
	ds_read_b32 v76, v76 offset:16656
	s_waitcnt lgkmcnt(1)
	v_cndmask_b32_e32 v224, 0, v77, vcc
	s_waitcnt lgkmcnt(0)
	v_cndmask_b32_e32 v88, 0, v76, vcc
.Lkd_22:
.LBB0_699:
	s_cmpk_lt_i32 s0, 0x581
	v_mov_b32_e32 v87, 0
	s_cbranch_scc1 .LBB0_701
	s_cmpk_lt_i32 s0, 0x5c0
	s_cbranch_scc1 .Lkg_23
	ds_read_b32 v223, v255 offset:14080
	ds_read_b32 v87, v255 offset:22288
	s_branch .Lkd_23
.Lkg_23:
	v_cmp_gt_i32_e32 vcc, s0, v203
	s_nop 1
	v_cndmask_b32_e32 v76, 0, v203, vcc
	v_lshl_add_u32 v76, v76, 2, s7
	ds_read_b32 v77, v76 offset:8448
	ds_read_b32 v76, v76 offset:16656
	s_waitcnt lgkmcnt(1)
	v_cndmask_b32_e32 v223, 0, v77, vcc
	s_waitcnt lgkmcnt(0)
	v_cndmask_b32_e32 v87, 0, v76, vcc
.Lkd_23:
.LBB0_701:
	v_mov_b32_e32 v221, 0
	s_cmpk_lt_i32 s0, 0x5c1
	v_mov_b32_e32 v222, 0
	v_mov_b32_e32 v86, 0
	s_cbranch_scc1 .LBB0_703
	s_cmpk_lt_i32 s0, 0x600
	s_cbranch_scc1 .Lkg_24
	ds_read_b32 v222, v255 offset:14336
	ds_read_b32 v86, v255 offset:22544
	s_branch .Lkd_24
.Lkg_24:
	v_cmp_gt_i32_e32 vcc, s0, v204
	s_nop 1
	v_cndmask_b32_e32 v76, 0, v204, vcc
	v_lshl_add_u32 v76, v76, 2, s7
	ds_read_b32 v77, v76 offset:8448
	ds_read_b32 v76, v76 offset:16656
	s_waitcnt lgkmcnt(1)
	v_cndmask_b32_e32 v222, 0, v77, vcc
	s_waitcnt lgkmcnt(0)
	v_cndmask_b32_e32 v86, 0, v76, vcc
.Lkd_24:
.LBB0_703:
	s_cmpk_gt_i32 s0, 0x600
	s_cselect_b64 s[14:15], -1, 0
	s_cmpk_lt_i32 s0, 0x601
	v_mov_b32_e32 v85, 0
	s_cbranch_scc1 .LBB0_705
	s_cmpk_lt_i32 s0, 0x640
	s_cbranch_scc1 .Lkg_25
	ds_read_b32 v221, v255 offset:14592
	ds_read_b32 v85, v255 offset:22800
	s_branch .Lkd_25
.Lkg_25:
	v_cmp_gt_i32_e32 vcc, s0, v205
	s_nop 1
	v_cndmask_b32_e32 v76, 0, v205, vcc
	v_lshl_add_u32 v76, v76, 2, s7
	ds_read_b32 v77, v76 offset:8448
	ds_read_b32 v76, v76 offset:16656
	s_waitcnt lgkmcnt(1)
	v_cndmask_b32_e32 v221, 0, v77, vcc
	s_waitcnt lgkmcnt(0)
	v_cndmask_b32_e32 v85, 0, v76, vcc
.Lkd_25:
.LBB0_705:
	v_mov_b32_e32 v219, 0
	s_cmpk_lt_i32 s0, 0x641
	v_mov_b32_e32 v220, 0
	v_mov_b32_e32 v84, 0
	s_cbranch_scc1 .LBB0_707
	s_cmpk_lt_i32 s0, 0x680
	s_cbranch_scc1 .Lkg_26
	ds_read_b32 v220, v255 offset:14848
	ds_read_b32 v84, v255 offset:23056
	s_branch .Lkd_26
.Lkg_26:
	v_cmp_gt_i32_e32 vcc, s0, v206
	s_nop 1
	v_cndmask_b32_e32 v76, 0, v206, vcc
	v_lshl_add_u32 v76, v76, 2, s7
	ds_read_b32 v77, v76 offset:8448
	ds_read_b32 v76, v76 offset:16656
	s_waitcnt lgkmcnt(1)
	v_cndmask_b32_e32 v220, 0, v77, vcc
	s_waitcnt lgkmcnt(0)
	v_cndmask_b32_e32 v84, 0, v76, vcc
.Lkd_26:
.LBB0_707:
	s_cmpk_lt_i32 s0, 0x681
	v_mov_b32_e32 v83, 0
	s_cbranch_scc1 .LBB0_709
	s_cmpk_lt_i32 s0, 0x6c0
	s_cbranch_scc1 .Lkg_27
	ds_read_b32 v219, v255 offset:15104
	ds_read_b32 v83, v255 offset:23312
	s_branch .Lkd_27
.Lkg_27:
	v_cmp_gt_i32_e32 vcc, s0, v207
	s_nop 1
	v_cndmask_b32_e32 v76, 0, v207, vcc
	v_lshl_add_u32 v76, v76, 2, s7
	ds_read_b32 v77, v76 offset:8448
	ds_read_b32 v76, v76 offset:16656
	s_waitcnt lgkmcnt(1)
	v_cndmask_b32_e32 v219, 0, v77, vcc
	s_waitcnt lgkmcnt(0)
	v_cndmask_b32_e32 v83, 0, v76, vcc
.Lkd_27:
.LBB0_709:
	v_mov_b32_e32 v217, 0
	s_cmpk_lt_i32 s0, 0x6c1
	v_mov_b32_e32 v218, 0
	v_mov_b32_e32 v82, 0
	s_cbranch_scc1 .LBB0_711
	s_cmpk_lt_i32 s0, 0x700
	s_cbranch_scc1 .Lkg_28
	ds_read_b32 v218, v255 offset:15360
	ds_read_b32 v82, v255 offset:23568
	s_branch .Lkd_28
.Lkg_28:
	v_cmp_gt_i32_e32 vcc, s0, v208
	s_nop 1
	v_cndmask_b32_e32 v76, 0, v208, vcc
	v_lshl_add_u32 v76, v76, 2, s7
	ds_read_b32 v77, v76 offset:8448
	ds_read_b32 v76, v76 offset:16656
	s_waitcnt lgkmcnt(1)
	v_cndmask_b32_e32 v218, 0, v77, vcc
	s_waitcnt lgkmcnt(0)
	v_cndmask_b32_e32 v82, 0, v76, vcc
.Lkd_28:
.LBB0_711:
	s_cmpk_lt_i32 s0, 0x701
	v_mov_b32_e32 v81, 0
	s_cbranch_scc1 .LBB0_713
	s_cmpk_lt_i32 s0, 0x740
	s_cbranch_scc1 .Lkg_29
	ds_read_b32 v217, v255 offset:15616
	ds_read_b32 v81, v255 offset:23824
	s_branch .Lkd_29
.Lkg_29:
	v_cmp_gt_i32_e32 vcc, s0, v209
	s_nop 1
	v_cndmask_b32_e32 v76, 0, v209, vcc
	v_lshl_add_u32 v76, v76, 2, s7
	ds_read_b32 v77, v76 offset:8448
	ds_read_b32 v76, v76 offset:16656
	s_waitcnt lgkmcnt(1)
	v_cndmask_b32_e32 v217, 0, v77, vcc
	s_waitcnt lgkmcnt(0)
	v_cndmask_b32_e32 v81, 0, v76, vcc
.Lkd_29:
.LBB0_713:
	v_mov_b32_e32 v77, 0
	s_cmpk_lt_i32 s0, 0x741
	v_mov_b32_e32 v216, 0
	v_mov_b32_e32 v80, 0
	s_cbranch_scc1 .LBB0_732
	s_cmpk_lt_i32 s0, 0x780
	s_cbranch_scc1 .Lkg_30
	ds_read_b32 v216, v255 offset:15872
	ds_read_b32 v80, v255 offset:24080
	s_branch .Lkd_30
.Lkg_30:
	v_cmp_gt_i32_e32 vcc, s0, v210
	s_nop 1
	v_cndmask_b32_e32 v76, 0, v210, vcc
	v_lshl_add_u32 v76, v76, 2, s7
	ds_read_b32 v78, v76 offset:8448
	ds_read_b32 v76, v76 offset:16656
	s_waitcnt lgkmcnt(1)
	v_cndmask_b32_e32 v216, 0, v78, vcc
	s_waitcnt lgkmcnt(0)
	v_cndmask_b32_e32 v80, 0, v76, vcc
.Lkd_30:
	s_cmpk_lt_i32 s0, 0x781
	v_mov_b32_e32 v79, 0
	s_cbranch_scc0 .LBB0_733

.LBB0_716:
	s_cmpk_lt_i32 s0, 0x800
	s_cbranch_scc1 .Lkg_31
	ds_read_b32 v76, v255 offset:16384
	ds_read_b32 v78, v255 offset:24592
	s_branch .Lkd_31

.Lkd_31:
.LBB0_717:
	s_waitcnt lgkmcnt(0)
	v_readlane_b32 s0, v254, 36
	s_cmp_lt_i32 s79, s0
	s_cbranch_scc1 .LBB0_734
	s_mov_b32 s2, 31
	s_mov_b64 s[16:17], 0
	s_movk_i32 s3, 0x800
	s_mov_b32 s1, 0
	s_mov_b32 s0, 0
	s_movk_i32 s20, 0x800
	s_mov_b64 s[18:19], 0
	s_branch .LBB0_720

.LBB0_733:
	s_cmpk_lt_i32 s0, 0x7c0
	s_cbranch_scc1 .Lkg_32
	ds_read_b32 v77, v255 offset:16128
	ds_read_b32 v79, v255 offset:24336
	s_branch .Lkd_32

.Lkd_32:
	v_mov_b32_e32 v76, 0
	s_cmpk_lt_i32 s0, 0x7c1
	v_mov_b32_e32 v78, 0
	s_cbranch_scc0 .LBB0_716
	s_branch .LBB0_717

.LBB0_1661:
	s_xor_b64 s[0:1], s[0:1], -1
	v_writelane_b32 v254, s0, 34
	s_waitcnt lgkmcnt(0)
	s_barrier
	v_lshl_add_u32 v255, v130, 2, s97
	v_writelane_b32 v254, s1, 35
	s_add_i32 s0, s93, 16
	s_cmp_gt_i32 s0, 0
	s_cselect_b64 s[4:5], -1, 0
	s_cmp_lt_i32 s0, 1
	s_cbranch_scc1 .LBB0_1663
	s_cmpk_lt_i32 s0, 0x40
	s_cbranch_scc1 .Lkg_33
	ds_read_b32 v241, v255 offset:8448
	ds_read_b32 v211, v255 offset:16656
	s_branch .Lkd_33
.Lkg_33:
	v_cmp_gt_i32_e32 vcc, s0, v130
	s_nop 1
	v_cndmask_b32_e32 v76, 0, v130, vcc
	v_lshl_add_u32 v76, v76, 2, s97
	ds_read_b32 v77, v76 offset:8448
	ds_read_b32 v76, v76 offset:16656
	s_waitcnt lgkmcnt(1)
	v_cndmask_b32_e32 v241, 0, v77, vcc
	s_waitcnt lgkmcnt(0)
	v_cndmask_b32_e32 v211, 0, v76, vcc
.Lkd_33:
	s_branch .LBB0_1664
.LBB0_1663:
	v_mov_b32_e32 v241, 0
	v_mov_b32_e32 v211, 0
.LBB0_1664:
	v_mov_b32_e32 v239, 0
	s_cmpk_lt_i32 s0, 0x41
	v_mov_b32_e32 v240, 0
	v_mov_b32_e32 v108, 0
	s_cbranch_scc1 .LBB0_1666
	s_cmpk_lt_i32 s0, 0x80
	s_cbranch_scc1 .Lkg_34
	ds_read_b32 v240, v255 offset:8704
	ds_read_b32 v108, v255 offset:16912
	s_branch .Lkd_34
.Lkg_34:
	v_cmp_gt_i32_e32 vcc, s0, v167
	s_nop 1
	v_cndmask_b32_e32 v76, 0, v167, vcc
	v_lshl_add_u32 v76, v76, 2, s97
	ds_read_b32 v77, v76 offset:8448
	ds_read_b32 v76, v76 offset:16656
	s_waitcnt lgkmcnt(1)
	v_cndmask_b32_e32 v240, 0, v77, vcc
	s_waitcnt lgkmcnt(0)
	v_cndmask_b32_e32 v108, 0, v76, vcc
.Lkd_34:
.LBB0_1666:
	s_cmpk_lt_i32 s0, 0x81
	v_mov_b32_e32 v107, 0
	s_cbranch_scc1 .LBB0_1668
	s_cmpk_lt_i32 s0, 0xc0
	s_cbranch_scc1 .Lkg_35
	ds_read_b32 v239, v255 offset:8960
	ds_read_b32 v107, v255 offset:17168
	s_branch .Lkd_35
.Lkg_35:
	v_cmp_gt_i32_e32 vcc, s0, v168
	s_nop 1
	v_cndmask_b32_e32 v76, 0, v168, vcc
	v_lshl_add_u32 v76, v76, 2, s97
	ds_read_b32 v77, v76 offset:8448
	ds_read_b32 v76, v76 offset:16656
	s_waitcnt lgkmcnt(1)
	v_cndmask_b32_e32 v239, 0, v77, vcc
	s_waitcnt lgkmcnt(0)
	v_cndmask_b32_e32 v107, 0, v76, vcc
.Lkd_35:
.LBB0_1668:
	v_mov_b32_e32 v237, 0
	s_cmpk_lt_i32 s0, 0xc1
	v_mov_b32_e32 v238, 0
	v_mov_b32_e32 v106, 0
	s_cbranch_scc1 .LBB0_1670
	s_cmpk_lt_i32 s0, 0x100
	s_cbranch_scc1 .Lkg_36
	ds_read_b32 v238, v255 offset:9216
	ds_read_b32 v106, v255 offset:17424
	s_branch .Lkd_36
.Lkg_36:
	v_cmp_gt_i32_e32 vcc, s0, v169
	s_nop 1
	v_cndmask_b32_e32 v76, 0, v169, vcc
	v_lshl_add_u32 v76, v76, 2, s97
	ds_read_b32 v77, v76 offset:8448
	ds_read_b32 v76, v76 offset:16656
	s_waitcnt lgkmcnt(1)
	v_cndmask_b32_e32 v238, 0, v77, vcc
	s_waitcnt lgkmcnt(0)
	v_cndmask_b32_e32 v106, 0, v76, vcc
.Lkd_36:
.LBB0_1670:
	s_cmpk_lt_i32 s0, 0x101
	v_mov_b32_e32 v105, 0
	s_cbranch_scc1 .LBB0_1672
	s_cmpk_lt_i32 s0, 0x140
	s_cbranch_scc1 .Lkg_37
	ds_read_b32 v237, v255 offset:9472
	ds_read_b32 v105, v255 offset:17680
	s_branch .Lkd_37
.Lkg_37:
	v_cmp_gt_i32_e32 vcc, s0, v170
	s_nop 1
	v_cndmask_b32_e32 v76, 0, v170, vcc
	v_lshl_add_u32 v76, v76, 2, s97
	ds_read_b32 v77, v76 offset:8448
	ds_read_b32 v76, v76 offset:16656
	s_waitcnt lgkmcnt(1)
	v_cndmask_b32_e32 v237, 0, v77, vcc
	s_waitcnt lgkmcnt(0)
	v_cndmask_b32_e32 v105, 0, v76, vcc
.Lkd_37:
.LBB0_1672:
	v_mov_b32_e32 v235, 0
	s_cmpk_lt_i32 s0, 0x141
	v_mov_b32_e32 v236, 0
	v_mov_b32_e32 v104, 0
	s_cbranch_scc1 .LBB0_1674
	s_cmpk_lt_i32 s0, 0x180
	s_cbranch_scc1 .Lkg_38
	ds_read_b32 v236, v255 offset:9728
	ds_read_b32 v104, v255 offset:17936
	s_branch .Lkd_38
.Lkg_38:
	v_cmp_gt_i32_e32 vcc, s0, v171
	s_nop 1
	v_cndmask_b32_e32 v76, 0, v171, vcc
	v_lshl_add_u32 v76, v76, 2, s97
	ds_read_b32 v77, v76 offset:8448
	ds_read_b32 v76, v76 offset:16656
	s_waitcnt lgkmcnt(1)
	v_cndmask_b32_e32 v236, 0, v77, vcc
	s_waitcnt lgkmcnt(0)
	v_cndmask_b32_e32 v104, 0, v76, vcc
.Lkd_38:
.LBB0_1674:
	s_cmpk_lt_i32 s0, 0x181
	v_mov_b32_e32 v103, 0
	s_cbranch_scc1 .LBB0_1676
	s_cmpk_lt_i32 s0, 0x1c0
	s_cbranch_scc1 .Lkg_39
	ds_read_b32 v235, v255 offset:9984
	ds_read_b32 v103, v255 offset:18192
	s_branch .Lkd_39
.Lkg_39:
	v_cmp_gt_i32_e32 vcc, s0, v172
	s_nop 1
	v_cndmask_b32_e32 v76, 0, v172, vcc
	v_lshl_add_u32 v76, v76, 2, s97
	ds_read_b32 v77, v76 offset:8448
	ds_read_b32 v76, v76 offset:16656
	s_waitcnt lgkmcnt(1)
	v_cndmask_b32_e32 v235, 0, v77, vcc
	s_waitcnt lgkmcnt(0)
	v_cndmask_b32_e32 v103, 0, v76, vcc
.Lkd_39:
.LBB0_1676:
	v_mov_b32_e32 v233, 0
	s_cmpk_lt_i32 s0, 0x1c1
	v_mov_b32_e32 v234, 0
	v_mov_b32_e32 v102, 0
	s_cbranch_scc1 .LBB0_1678
	s_cmpk_lt_i32 s0, 0x200
	s_cbranch_scc1 .Lkg_40
	ds_read_b32 v234, v255 offset:10240
	ds_read_b32 v102, v255 offset:18448
	s_branch .Lkd_40
.Lkg_40:
	v_cmp_gt_i32_e32 vcc, s0, v173
	s_nop 1
	v_cndmask_b32_e32 v76, 0, v173, vcc
	v_lshl_add_u32 v76, v76, 2, s97
	ds_read_b32 v77, v76 offset:8448
	ds_read_b32 v76, v76 offset:16656
	s_waitcnt lgkmcnt(1)
	v_cndmask_b32_e32 v234, 0, v77, vcc
	s_waitcnt lgkmcnt(0)
	v_cndmask_b32_e32 v102, 0, v76, vcc
.Lkd_40:
.LBB0_1678:
	s_cmpk_gt_i32 s0, 0x200
	s_cselect_b64 s[8:9], -1, 0
	s_cmpk_lt_i32 s0, 0x201
	v_mov_b32_e32 v101, 0
	s_cbranch_scc1 .LBB0_1680
	s_cmpk_lt_i32 s0, 0x240
	s_cbranch_scc1 .Lkg_41
	ds_read_b32 v233, v255 offset:10496
	ds_read_b32 v101, v255 offset:18704
	s_branch .Lkd_41
.Lkg_41:
	v_cmp_gt_i32_e32 vcc, s0, v174
	s_nop 1
	v_cndmask_b32_e32 v76, 0, v174, vcc
	v_lshl_add_u32 v76, v76, 2, s97
	ds_read_b32 v77, v76 offset:8448
	ds_read_b32 v76, v76 offset:16656
	s_waitcnt lgkmcnt(1)
	v_cndmask_b32_e32 v233, 0, v77, vcc
	s_waitcnt lgkmcnt(0)
	v_cndmask_b32_e32 v101, 0, v76, vcc
.Lkd_41:
.LBB0_1680:
	v_mov_b32_e32 v231, 0
	s_cmpk_lt_i32 s0, 0x241
	v_mov_b32_e32 v232, 0
	v_mov_b32_e32 v100, 0
	s_cbranch_scc1 .LBB0_1682
	s_cmpk_lt_i32 s0, 0x280
	s_cbranch_scc1 .Lkg_42
	ds_read_b32 v232, v255 offset:10752
	ds_read_b32 v100, v255 offset:18960
	s_branch .Lkd_42
.Lkg_42:
	v_cmp_gt_i32_e32 vcc, s0, v175
	s_nop 1
	v_cndmask_b32_e32 v76, 0, v175, vcc
	v_lshl_add_u32 v76, v76, 2, s97
	ds_read_b32 v77, v76 offset:8448
	ds_read_b32 v76, v76 offset:16656
	s_waitcnt lgkmcnt(1)
	v_cndmask_b32_e32 v232, 0, v77, vcc
	s_waitcnt lgkmcnt(0)
	v_cndmask_b32_e32 v100, 0, v76, vcc
.Lkd_42:
.LBB0_1682:
	s_cmpk_lt_i32 s0, 0x281
	v_mov_b32_e32 v99, 0
	s_cbranch_scc1 .LBB0_1684
	s_cmpk_lt_i32 s0, 0x2c0
	s_cbranch_scc1 .Lkg_43
	ds_read_b32 v231, v255 offset:11008
	ds_read_b32 v99, v255 offset:19216
	s_branch .Lkd_43
.Lkg_43:
	v_cmp_gt_i32_e32 vcc, s0, v176
	s_nop 1
	v_cndmask_b32_e32 v76, 0, v176, vcc
	v_lshl_add_u32 v76, v76, 2, s97
	ds_read_b32 v77, v76 offset:8448
	ds_read_b32 v76, v76 offset:16656
	s_waitcnt lgkmcnt(1)
	v_cndmask_b32_e32 v231, 0, v77, vcc
	s_waitcnt lgkmcnt(0)
	v_cndmask_b32_e32 v99, 0, v76, vcc
.Lkd_43:
.LBB0_1684:
	v_mov_b32_e32 v229, 0
	s_cmpk_lt_i32 s0, 0x2c1
	v_mov_b32_e32 v230, 0
	v_mov_b32_e32 v98, 0
	s_cbranch_scc1 .LBB0_1686
	s_cmpk_lt_i32 s0, 0x300
	s_cbranch_scc1 .Lkg_44
	ds_read_b32 v230, v255 offset:11264
	ds_read_b32 v98, v255 offset:19472
	s_branch .Lkd_44
.Lkg_44:
	v_cmp_gt_i32_e32 vcc, s0, v177
	s_nop 1
	v_cndmask_b32_e32 v76, 0, v177, vcc
	v_lshl_add_u32 v76, v76, 2, s97
	ds_read_b32 v77, v76 offset:8448
	ds_read_b32 v76, v76 offset:16656
	s_waitcnt lgkmcnt(1)
	v_cndmask_b32_e32 v230, 0, v77, vcc
	s_waitcnt lgkmcnt(0)
	v_cndmask_b32_e32 v98, 0, v76, vcc
.Lkd_44:
.LBB0_1686:
	s_cmpk_lt_i32 s0, 0x301
	v_mov_b32_e32 v97, 0
	s_cbranch_scc1 .LBB0_1688
	s_cmpk_lt_i32 s0, 0x340
	s_cbranch_scc1 .Lkg_45
	ds_read_b32 v229, v255 offset:11520
	ds_read_b32 v97, v255 offset:19728
	s_branch .Lkd_45
.Lkg_45:
	v_cmp_gt_i32_e32 vcc, s0, v178
	s_nop 1
	v_cndmask_b32_e32 v76, 0, v178, vcc
	v_lshl_add_u32 v76, v76, 2, s97
	ds_read_b32 v77, v76 offset:8448
	ds_read_b32 v76, v76 offset:16656
	s_waitcnt lgkmcnt(1)
	v_cndmask_b32_e32 v229, 0, v77, vcc
	s_waitcnt lgkmcnt(0)
	v_cndmask_b32_e32 v97, 0, v76, vcc
.Lkd_45:
.LBB0_1688:
	v_mov_b32_e32 v227, 0
	s_cmpk_lt_i32 s0, 0x341
	v_mov_b32_e32 v228, 0
	v_mov_b32_e32 v96, 0
	s_cbranch_scc1 .LBB0_1690
	s_cmpk_lt_i32 s0, 0x380
	s_cbranch_scc1 .Lkg_46
	ds_read_b32 v228, v255 offset:11776
	ds_read_b32 v96, v255 offset:19984
	s_branch .Lkd_46
.Lkg_46:
	v_cmp_gt_i32_e32 vcc, s0, v179
	s_nop 1
	v_cndmask_b32_e32 v76, 0, v179, vcc
	v_lshl_add_u32 v76, v76, 2, s97
	ds_read_b32 v77, v76 offset:8448
	ds_read_b32 v76, v76 offset:16656
	s_waitcnt lgkmcnt(1)
	v_cndmask_b32_e32 v228, 0, v77, vcc
	s_waitcnt lgkmcnt(0)
	v_cndmask_b32_e32 v96, 0, v76, vcc
.Lkd_46:
.LBB0_1690:
	s_cmpk_lt_i32 s0, 0x381
	v_mov_b32_e32 v95, 0
	s_cbranch_scc1 .LBB0_1692
	s_cmpk_lt_i32 s0, 0x3c0
	s_cbranch_scc1 .Lkg_47
	ds_read_b32 v227, v255 offset:12032
	ds_read_b32 v95, v255 offset:20240
	s_branch .Lkd_47
.Lkg_47:
	v_cmp_gt_i32_e32 vcc, s0, v180
	s_nop 1
	v_cndmask_b32_e32 v76, 0, v180, vcc
	v_lshl_add_u32 v76, v76, 2, s97
	ds_read_b32 v77, v76 offset:8448
	ds_read_b32 v76, v76 offset:16656
	s_waitcnt lgkmcnt(1)
	v_cndmask_b32_e32 v227, 0, v77, vcc
	s_waitcnt lgkmcnt(0)
	v_cndmask_b32_e32 v95, 0, v76, vcc
.Lkd_47:
.LBB0_1692:
	v_mov_b32_e32 v225, 0
	s_cmpk_lt_i32 s0, 0x3c1
	v_mov_b32_e32 v226, 0
	v_mov_b32_e32 v94, 0
	s_cbranch_scc1 .LBB0_1694
	s_cmpk_lt_i32 s0, 0x400
	s_cbranch_scc1 .Lkg_48
	ds_read_b32 v226, v255 offset:12288
	ds_read_b32 v94, v255 offset:20496
	s_branch .Lkd_48
.Lkg_48:
	v_cmp_gt_i32_e32 vcc, s0, v181
	s_nop 1
	v_cndmask_b32_e32 v76, 0, v181, vcc
	v_lshl_add_u32 v76, v76, 2, s97
	ds_read_b32 v77, v76 offset:8448
	ds_read_b32 v76, v76 offset:16656
	s_waitcnt lgkmcnt(1)
	v_cndmask_b32_e32 v226, 0, v77, vcc
	s_waitcnt lgkmcnt(0)
	v_cndmask_b32_e32 v94, 0, v76, vcc
.Lkd_48:
.LBB0_1694:
	s_cmpk_gt_i32 s0, 0x400
	s_cselect_b64 s[10:11], -1, 0
	s_cmpk_lt_i32 s0, 0x401
	v_mov_b32_e32 v93, 0
	s_cbranch_scc1 .LBB0_1696
	s_cmpk_lt_i32 s0, 0x440
	s_cbranch_scc1 .Lkg_49
	ds_read_b32 v225, v255 offset:12544
	ds_read_b32 v93, v255 offset:20752
	s_branch .Lkd_49
.Lkg_49:
	v_cmp_gt_i32_e32 vcc, s0, v182
	s_nop 1
	v_cndmask_b32_e32 v76, 0, v182, vcc
	v_lshl_add_u32 v76, v76, 2, s97
	ds_read_b32 v77, v76 offset:8448
	ds_read_b32 v76, v76 offset:16656
	s_waitcnt lgkmcnt(1)
	v_cndmask_b32_e32 v225, 0, v77, vcc
	s_waitcnt lgkmcnt(0)
	v_cndmask_b32_e32 v93, 0, v76, vcc
.Lkd_49:
.LBB0_1696:
	v_mov_b32_e32 v223, 0
	s_cmpk_lt_i32 s0, 0x441
	v_mov_b32_e32 v224, 0
	v_mov_b32_e32 v92, 0
	s_cbranch_scc1 .LBB0_1698
	s_cmpk_lt_i32 s0, 0x480
	s_cbranch_scc1 .Lkg_50
	ds_read_b32 v224, v255 offset:12800
	ds_read_b32 v92, v255 offset:21008
	s_branch .Lkd_50
.Lkg_50:
	v_cmp_gt_i32_e32 vcc, s0, v183
	s_nop 1
	v_cndmask_b32_e32 v76, 0, v183, vcc
	v_lshl_add_u32 v76, v76, 2, s97
	ds_read_b32 v77, v76 offset:8448
	ds_read_b32 v76, v76 offset:16656
	s_waitcnt lgkmcnt(1)
	v_cndmask_b32_e32 v224, 0, v77, vcc
	s_waitcnt lgkmcnt(0)
	v_cndmask_b32_e32 v92, 0, v76, vcc
.Lkd_50:
.LBB0_1698:
	s_cmpk_lt_i32 s0, 0x481
	v_mov_b32_e32 v91, 0
	s_cbranch_scc1 .LBB0_1700
	s_cmpk_lt_i32 s0, 0x4c0
	s_cbranch_scc1 .Lkg_51
	ds_read_b32 v223, v255 offset:13056
	ds_read_b32 v91, v255 offset:21264
	s_branch .Lkd_51
.Lkg_51:
	v_cmp_gt_i32_e32 vcc, s0, v184
	s_nop 1
	v_cndmask_b32_e32 v76, 0, v184, vcc
	v_lshl_add_u32 v76, v76, 2, s97
	ds_read_b32 v77, v76 offset:8448
	ds_read_b32 v76, v76 offset:16656
	s_waitcnt lgkmcnt(1)
	v_cndmask_b32_e32 v223, 0, v77, vcc
	s_waitcnt lgkmcnt(0)
	v_cndmask_b32_e32 v91, 0, v76, vcc
.Lkd_51:
.LBB0_1700:
	v_mov_b32_e32 v221, 0
	s_cmpk_lt_i32 s0, 0x4c1
	v_mov_b32_e32 v222, 0
	v_mov_b32_e32 v90, 0
	s_cbranch_scc1 .LBB0_1702
	s_cmpk_lt_i32 s0, 0x500
	s_cbranch_scc1 .Lkg_52
	ds_read_b32 v222, v255 offset:13312
	ds_read_b32 v90, v255 offset:21520
	s_branch .Lkd_52
.Lkg_52:
	v_cmp_gt_i32_e32 vcc, s0, v185
	s_nop 1
	v_cndmask_b32_e32 v76, 0, v185, vcc
	v_lshl_add_u32 v76, v76, 2, s97
	ds_read_b32 v77, v76 offset:8448
	ds_read_b32 v76, v76 offset:16656
	s_waitcnt lgkmcnt(1)
	v_cndmask_b32_e32 v222, 0, v77, vcc
	s_waitcnt lgkmcnt(0)
	v_cndmask_b32_e32 v90, 0, v76, vcc
.Lkd_52:
.LBB0_1702:
	s_cmpk_lt_i32 s0, 0x501
	v_mov_b32_e32 v89, 0
	s_cbranch_scc1 .LBB0_1704
	s_cmpk_lt_i32 s0, 0x540
	s_cbranch_scc1 .Lkg_53
	ds_read_b32 v221, v255 offset:13568
	ds_read_b32 v89, v255 offset:21776
	s_branch .Lkd_53
.Lkg_53:
	v_cmp_gt_i32_e32 vcc, s0, v186
	s_nop 1
	v_cndmask_b32_e32 v76, 0, v186, vcc
	v_lshl_add_u32 v76, v76, 2, s97
	ds_read_b32 v77, v76 offset:8448
	ds_read_b32 v76, v76 offset:16656
	s_waitcnt lgkmcnt(1)
	v_cndmask_b32_e32 v221, 0, v77, vcc
	s_waitcnt lgkmcnt(0)
	v_cndmask_b32_e32 v89, 0, v76, vcc
.Lkd_53:
.LBB0_1704:
	v_mov_b32_e32 v219, 0
	s_cmpk_lt_i32 s0, 0x541
	v_mov_b32_e32 v220, 0
	v_mov_b32_e32 v88, 0
	s_cbranch_scc1 .LBB0_1706
	s_cmpk_lt_i32 s0, 0x580
	s_cbranch_scc1 .Lkg_54
	ds_read_b32 v220, v255 offset:13824
	ds_read_b32 v88, v255 offset:22032
	s_branch .Lkd_54
.Lkg_54:
	v_cmp_gt_i32_e32 vcc, s0, v187
	s_nop 1
	v_cndmask_b32_e32 v76, 0, v187, vcc
	v_lshl_add_u32 v76, v76, 2, s97
	ds_read_b32 v77, v76 offset:8448
	ds_read_b32 v76, v76 offset:16656
	s_waitcnt lgkmcnt(1)
	v_cndmask_b32_e32 v220, 0, v77, vcc
	s_waitcnt lgkmcnt(0)
	v_cndmask_b32_e32 v88, 0, v76, vcc
.Lkd_54:
.LBB0_1706:
	s_cmpk_lt_i32 s0, 0x581
	v_mov_b32_e32 v87, 0
	s_cbranch_scc1 .LBB0_1708
	s_cmpk_lt_i32 s0, 0x5c0
	s_cbranch_scc1 .Lkg_55
	ds_read_b32 v219, v255 offset:14080
	ds_read_b32 v87, v255 offset:22288
	s_branch .Lkd_55
.Lkg_55:
	v_cmp_gt_i32_e32 vcc, s0, v191
	s_nop 1
	v_cndmask_b32_e32 v76, 0, v191, vcc
	v_lshl_add_u32 v76, v76, 2, s97
	ds_read_b32 v77, v76 offset:8448
	ds_read_b32 v76, v76 offset:16656
	s_waitcnt lgkmcnt(1)
	v_cndmask_b32_e32 v219, 0, v77, vcc
	s_waitcnt lgkmcnt(0)
	v_cndmask_b32_e32 v87, 0, v76, vcc
.Lkd_55:
.LBB0_1708:
	v_mov_b32_e32 v217, 0
	s_cmpk_lt_i32 s0, 0x5c1
	v_mov_b32_e32 v218, 0
	v_mov_b32_e32 v86, 0
	s_cbranch_scc1 .LBB0_1710
	s_cmpk_lt_i32 s0, 0x600
	s_cbranch_scc1 .Lkg_56
	ds_read_b32 v218, v255 offset:14336
	ds_read_b32 v86, v255 offset:22544
	s_branch .Lkd_56
.Lkg_56:
	v_cmp_gt_i32_e32 vcc, s0, v200
	s_nop 1
	v_cndmask_b32_e32 v76, 0, v200, vcc
	v_lshl_add_u32 v76, v76, 2, s97
	ds_read_b32 v77, v76 offset:8448
	ds_read_b32 v76, v76 offset:16656
	s_waitcnt lgkmcnt(1)
	v_cndmask_b32_e32 v218, 0, v77, vcc
	s_waitcnt lgkmcnt(0)
	v_cndmask_b32_e32 v86, 0, v76, vcc
.Lkd_56:
.LBB0_1710:
	s_cmpk_gt_i32 s0, 0x600
	s_cselect_b64 s[12:13], -1, 0
	s_cmpk_lt_i32 s0, 0x601
	v_mov_b32_e32 v85, 0
	s_cbranch_scc1 .LBB0_1712
	s_cmpk_lt_i32 s0, 0x640
	s_cbranch_scc1 .Lkg_57
	ds_read_b32 v217, v255 offset:14592
	ds_read_b32 v85, v255 offset:22800
	s_branch .Lkd_57
.Lkg_57:
	v_cmp_gt_i32_e32 vcc, s0, v201
	s_nop 1
	v_cndmask_b32_e32 v76, 0, v201, vcc
	v_lshl_add_u32 v76, v76, 2, s97
	ds_read_b32 v77, v76 offset:8448
	ds_read_b32 v76, v76 offset:16656
	s_waitcnt lgkmcnt(1)
	v_cndmask_b32_e32 v217, 0, v77, vcc
	s_waitcnt lgkmcnt(0)
	v_cndmask_b32_e32 v85, 0, v76, vcc
.Lkd_57:
.LBB0_1712:
	v_mov_b32_e32 v215, 0
	s_cmpk_lt_i32 s0, 0x641
	v_mov_b32_e32 v216, 0
	v_mov_b32_e32 v84, 0
	s_cbranch_scc1 .LBB0_1714
	s_cmpk_lt_i32 s0, 0x680
	s_cbranch_scc1 .Lkg_58
	ds_read_b32 v216, v255 offset:14848
	ds_read_b32 v84, v255 offset:23056
	s_branch .Lkd_58
.Lkg_58:
	v_cmp_gt_i32_e32 vcc, s0, v202
	s_nop 1
	v_cndmask_b32_e32 v76, 0, v202, vcc
	v_lshl_add_u32 v76, v76, 2, s97
	ds_read_b32 v77, v76 offset:8448
	ds_read_b32 v76, v76 offset:16656
	s_waitcnt lgkmcnt(1)
	v_cndmask_b32_e32 v216, 0, v77, vcc
	s_waitcnt lgkmcnt(0)
	v_cndmask_b32_e32 v84, 0, v76, vcc
.Lkd_58:
.LBB0_1714:
	s_cmpk_lt_i32 s0, 0x681
	v_mov_b32_e32 v83, 0
	s_cbranch_scc1 .LBB0_1716
	s_cmpk_lt_i32 s0, 0x6c0
	s_cbranch_scc1 .Lkg_59
	ds_read_b32 v215, v255 offset:15104
	ds_read_b32 v83, v255 offset:23312
	s_branch .Lkd_59
.Lkg_59:
	v_cmp_gt_i32_e32 vcc, s0, v203
	s_nop 1
	v_cndmask_b32_e32 v76, 0, v203, vcc
	v_lshl_add_u32 v76, v76, 2, s97
	ds_read_b32 v77, v76 offset:8448
	ds_read_b32 v76, v76 offset:16656
	s_waitcnt lgkmcnt(1)
	v_cndmask_b32_e32 v215, 0, v77, vcc
	s_waitcnt lgkmcnt(0)
	v_cndmask_b32_e32 v83, 0, v76, vcc
.Lkd_59:
.LBB0_1716:
	v_mov_b32_e32 v213, 0
	s_cmpk_lt_i32 s0, 0x6c1
	v_mov_b32_e32 v214, 0
	v_mov_b32_e32 v82, 0
	s_cbranch_scc1 .LBB0_1718
	s_cmpk_lt_i32 s0, 0x700
	s_cbranch_scc1 .Lkg_60
	ds_read_b32 v214, v255 offset:15360
	ds_read_b32 v82, v255 offset:23568
	s_branch .Lkd_60
.Lkg_60:
	v_cmp_gt_i32_e32 vcc, s0, v204
	s_nop 1
	v_cndmask_b32_e32 v76, 0, v204, vcc
	v_lshl_add_u32 v76, v76, 2, s97
	ds_read_b32 v77, v76 offset:8448
	ds_read_b32 v76, v76 offset:16656
	s_waitcnt lgkmcnt(1)
	v_cndmask_b32_e32 v214, 0, v77, vcc
	s_waitcnt lgkmcnt(0)
	v_cndmask_b32_e32 v82, 0, v76, vcc
.Lkd_60:
.LBB0_1718:
	s_cmpk_lt_i32 s0, 0x701
	v_mov_b32_e32 v81, 0
	s_cbranch_scc1 .LBB0_1720
	s_cmpk_lt_i32 s0, 0x740
	s_cbranch_scc1 .Lkg_61
	ds_read_b32 v213, v255 offset:15616
	ds_read_b32 v81, v255 offset:23824
	s_branch .Lkd_61
.Lkg_61:
	v_cmp_gt_i32_e32 vcc, s0, v205
	s_nop 1
	v_cndmask_b32_e32 v76, 0, v205, vcc
	v_lshl_add_u32 v76, v76, 2, s97
	ds_read_b32 v77, v76 offset:8448
	ds_read_b32 v76, v76 offset:16656
	s_waitcnt lgkmcnt(1)
	v_cndmask_b32_e32 v213, 0, v77, vcc
	s_waitcnt lgkmcnt(0)
	v_cndmask_b32_e32 v81, 0, v76, vcc
.Lkd_61:
.LBB0_1720:
	v_mov_b32_e32 v77, 0
	s_cmpk_lt_i32 s0, 0x741
	v_mov_b32_e32 v212, 0
	v_mov_b32_e32 v80, 0
	s_cbranch_scc1 .LBB0_1739
	s_cmpk_lt_i32 s0, 0x780
	s_cbranch_scc1 .Lkg_62
	ds_read_b32 v212, v255 offset:15872
	ds_read_b32 v80, v255 offset:24080
	s_branch .Lkd_62
.Lkg_62:
	v_cmp_gt_i32_e32 vcc, s0, v206
	s_nop 1
	v_cndmask_b32_e32 v76, 0, v206, vcc
	v_lshl_add_u32 v76, v76, 2, s97
	ds_read_b32 v78, v76 offset:8448
	ds_read_b32 v76, v76 offset:16656
	s_waitcnt lgkmcnt(1)
	v_cndmask_b32_e32 v212, 0, v78, vcc
	s_waitcnt lgkmcnt(0)
	v_cndmask_b32_e32 v80, 0, v76, vcc

.Lkd_63:
.LBB0_1724:
	s_waitcnt lgkmcnt(0)
	v_readlane_b32 s0, v254, 39
	s_cmp_lt_i32 s93, s0
	s_cbranch_scc1 .LBB0_1741
	s_mov_b32 s2, 31
	s_mov_b64 s[14:15], 0
	s_movk_i32 s3, 0x800
	s_mov_b32 s1, 0
	s_mov_b32 s0, 0
	s_movk_i32 s18, 0x800
	s_mov_b64 s[16:17], 0
	s_branch .LBB0_1727

	.amdhsa_kernel _Z4mega6Params
		.amdhsa_group_segment_fixed_size 0
		.amdhsa_private_segment_fixed_size 0
		.amdhsa_kernarg_size 352
		.amdhsa_user_sgpr_count 2
		.amdhsa_user_sgpr_dispatch_ptr 0
		.amdhsa_user_sgpr_queue_ptr 0
		.amdhsa_user_sgpr_kernarg_segment_ptr 1
		.amdhsa_user_sgpr_dispatch_id 0
		.amdhsa_user_sgpr_kernarg_preload_length 0
		.amdhsa_user_sgpr_kernarg_preload_offset 0
		.amdhsa_user_sgpr_private_segment_size 0
		.amdhsa_uses_dynamic_stack 0
		.amdhsa_enable_private_segment 0
		.amdhsa_system_sgpr_workgroup_id_x 1
		.amdhsa_system_sgpr_workgroup_id_y 0
		.amdhsa_system_sgpr_workgroup_id_z 0
		.amdhsa_system_sgpr_workgroup_info 0
		.amdhsa_system_vgpr_workitem_id 2
		.amdhsa_next_free_vgpr 256
		.amdhsa_next_free_sgpr 98
		.amdhsa_accum_offset 256
		.amdhsa_reserve_vcc 1
		.amdhsa_float_round_mode_32 0
		.amdhsa_float_round_mode_16_64 0
		.amdhsa_float_denorm_mode_32 3
		.amdhsa_float_denorm_mode_16_64 3
		.amdhsa_dx10_clamp 1
		.amdhsa_ieee_mode 1
		.amdhsa_fp16_overflow 0
		.amdhsa_tg_split 0
		.amdhsa_exception_fp_ieee_invalid_op 0
		.amdhsa_exception_fp_denorm_src 0
		.amdhsa_exception_fp_ieee_div_zero 0
		.amdhsa_exception_fp_ieee_overflow 0
		.amdhsa_exception_fp_ieee_underflow 0
		.amdhsa_exception_fp_ieee_inexact 0
		.amdhsa_exception_int_div_zero 0
	.end_amdhsa_kernel

amdhsa.kernels:
  - .agpr_count:     0
    .args:
      - .offset:         0
        .size:           96
        .value_kind:     by_value
      - .offset:         96
        .size:           4
        .value_kind:     hidden_block_count_x
      - .offset:         100
        .size:           4
        .value_kind:     hidden_block_count_y
      - .offset:         104
        .size:           4
        .value_kind:     hidden_block_count_z
      - .offset:         108
        .size:           2
        .value_kind:     hidden_group_size_x
      - .offset:         110
        .size:           2
        .value_kind:     hidden_group_size_y
      - .offset:         112
        .size:           2
        .value_kind:     hidden_group_size_z
      - .offset:         114
        .size:           2
        .value_kind:     hidden_remainder_x
      - .offset:         116
        .size:           2
        .value_kind:     hidden_remainder_y
      - .offset:         118
        .size:           2
        .value_kind:     hidden_remainder_z
      - .offset:         136
        .size:           8
        .value_kind:     hidden_global_offset_x
      - .offset:         144
        .size:           8
        .value_kind:     hidden_global_offset_y
      - .offset:         152
        .size:           8
        .value_kind:     hidden_global_offset_z
      - .offset:         160
        .size:           2
        .value_kind:     hidden_grid_dims
      - .offset:         184
        .size:           8
        .value_kind:     hidden_multigrid_sync_arg
      - .offset:         216
        .size:           4
        .value_kind:     hidden_dynamic_lds_size
    .group_segment_fixed_size: 0
    .kernarg_segment_align: 8
    .kernarg_segment_size: 352
    .language:       OpenCL C
    .language_version:
      - 2
      - 0
    .max_flat_workgroup_size: 512
    .name:           _Z4mega6Params
    .private_segment_fixed_size: 0
    .sgpr_count:     104
    .sgpr_spill_count: 87
    .symbol:         _Z4mega6Params.kd
    .uniform_work_group_size: 1
    .uses_dynamic_stack: false
    .vgpr_count:     256
    .vgpr_spill_count: 0
    .wavefront_size: 64
